# GQA loop: K-tile row addresses as loop-invariant per-lane pointer (computed once per item) + scalar row*stride offset; two v_mad_i64_i32 and two v_add per iteration replaced by two s_mul and two v_lsh
# baseline (speedup 1.0000x reference)
.LBB0_753:
	s_and_b64 vcc, exec, s[0:1]
	s_cbranch_vccz .LBB0_757
	s_waitcnt vmcnt(18)
	v_mov_b32_e32 v22, v179
	v_mov_b64_e32 v[8:9], s[66:67]
	v_and_b32_e32 v105, 31, v22
	v_ashrrev_i32_e32 v0, 1, v22
	v_and_b32_e32 v0, 0xffffffe0, v0
	v_or_b32_e32 v1, s4, v105
	v_add_u32_e32 v0, v1, v0
	v_bfe_u32 v23, v22, 5, 1
	v_mad_i64_i32 v[0:1], s[0:1], v0, s43, v[8:9]
	s_lshl_b32 s96, s3, 1
	v_lshl_add_u64 v[0:1], v[0:1], 0, s[96:97]
	v_lshlrev_b32_e32 v176, 4, v23
	v_lshl_add_u64 v[0:1], v[0:1], 0, v[176:177]
	v_ashrrev_i32_e32 v107, 3, v22
	s_mov_b32 s7, s95
	global_load_dwordx4 v[76:79], v[0:1], off offset:1536
	global_load_dwordx4 v[72:75], v[0:1], off offset:1568
	global_load_dwordx4 v[68:71], v[0:1], off offset:1600
	global_load_dwordx4 v[64:67], v[0:1], off offset:1632
	v_add_u32_e32 v0, s7, v107
	v_mad_i64_i32 v[0:1], s[0:1], v0, s43, v[8:9]
	s_lshl_b32 s96, s6, 1
	v_lshlrev_b32_e32 v2, 4, v22
	v_lshl_add_u64 v[0:1], v[0:1], 0, s[96:97]
	v_and_b32_e32 v98, 0x70, v2
	v_mov_b32_e32 v99, v177
	v_lshl_add_u64 v[0:1], v[0:1], 0, v[98:99]
	global_load_dwordx4 v[0:3], v[0:1], off
	s_movk_i32 s6, 0x2200
	v_mad_i64_i32 v[4:5], s[0:1], v107, s6, v[96:97]
	v_lshl_add_u64 v[4:5], v[4:5], 0, v[98:99]
	s_waitcnt vmcnt(20)
	v_add_u32_e32 v24, 0x100, v22
	global_load_dwordx4 v[4:7], v[4:5], off
	v_ashrrev_i32_e32 v108, 3, v24
	v_add_u32_e32 v10, s7, v108
	v_mad_i64_i32 v[8:9], s[0:1], v10, s43, v[8:9]
	v_lshl_add_u64 v[8:9], v[8:9], 0, s[96:97]
	v_lshl_add_u64 v[8:9], v[8:9], 0, v[98:99]
	global_load_dwordx4 v[8:11], v[8:9], off
	v_mad_i64_i32 v[12:13], s[0:1], v108, s6, v[96:97]
	v_lshl_add_u64 v[12:13], v[12:13], 0, v[98:99]
	global_load_dwordx4 v[12:15], v[12:13], off
	v_mad_u64_u32 v[20:21], s[0:1], v107, s42, v[98:99]
	v_mad_i64_i32 v[16:17], s[0:1], v107, s6, 0
	v_mad_i64_i32 v[18:19], s[0:1], v108, s6, 0
	v_or_b32_e32 v16, v16, v98
	v_or_b32_e32 v18, v18, v98
	v_lshlrev_b32_e32 v106, 3, v23
	v_lshlrev_b32_e32 v104, 2, v23
	v_add_u32_e32 v109, 64, v108
	v_add_u32_e32 v110, 64, v107
	s_movk_i32 s8, 0xff00
	s_movk_i32 s9, 0x4800
	s_mov_b64 s[10:11], 0x80
	v_readlane_b32 s12, v255, 5
	s_waitcnt vmcnt(3)
	ds_write_b128 v20, v[0:3]
	v_and_b32_e32 v0, -8, v22
	v_sub_u32_e32 v0, v20, v0
	v_add_u32_e32 v0, 0x4800, v0
	s_waitcnt vmcnt(2)
	ds_write2_b64 v0, v[4:5], v[6:7] offset1:1
	v_mad_u64_u32 v[0:1], s[0:1], v108, s42, v[98:99]
	s_add_u32 s0, s66, s96
	s_addc_u32 s1, s67, 0
	v_lshl_add_u64 v[96:97], s[0:1], 0, v[98:99]
	v_readlane_b32 s0, v255, 6
	v_and_b32_e32 v1, -8, v24
	s_add_i32 s0, s0, s5
	v_readlane_b32 s1, v254, 12
	s_waitcnt vmcnt(1)
	ds_write_b128 v0, v[8:11]
	v_sub_u32_e32 v0, v0, v1
	s_add_u32 s0, s1, s0
	v_readlane_b32 s1, v254, 13
	v_add_u32_e32 v0, 0x4800, v0
	s_addc_u32 s1, s1, 0
	v_mov_b32_e32 v99, 0
	s_waitcnt vmcnt(0)
	ds_write2_b64 v0, v[12:13], v[14:15] offset1:1
	v_lshl_add_u64 v[100:101], s[0:1], 0, v[16:17]
	v_lshl_add_u64 v[102:103], s[0:1], 0, v[18:19]
	s_mov_b32 s0, 0
	s_mov_b32 s5, 0
	v_mov_b32_e32 v0, 0
	v_mov_b32_e32 v1, v99
	v_mov_b32_e32 v2, v99
	v_mov_b32_e32 v3, v99
	v_mov_b32_e32 v4, v99
	v_mov_b32_e32 v5, v99
	v_mov_b32_e32 v6, v99
	v_mov_b32_e32 v7, v99
	v_mov_b32_e32 v8, v99
	v_mov_b32_e32 v9, v99
	v_mov_b32_e32 v10, v99
	v_mov_b32_e32 v11, v99
	v_mov_b32_e32 v12, v99
	v_mov_b32_e32 v13, v99
	v_mov_b32_e32 v14, v99
	v_mov_b32_e32 v15, v99
	v_mov_b32_e32 v16, 0
	v_mov_b32_e32 v17, v99
	v_mov_b32_e32 v18, v99
	v_mov_b32_e32 v19, v99
	v_mov_b32_e32 v20, v99
	v_mov_b32_e32 v21, v99
	v_mov_b32_e32 v22, v99
	v_mov_b32_e32 v23, v99
	v_mov_b32_e32 v24, v99
	v_mov_b32_e32 v25, v99
	v_mov_b32_e32 v26, v99
	v_mov_b32_e32 v27, v99
	v_mov_b32_e32 v28, v99
	v_mov_b32_e32 v29, v99
	v_mov_b32_e32 v30, v99
	v_mov_b32_e32 v31, v99
	s_waitcnt lgkmcnt(0)
	s_barrier
	v_mad_u32_u24 v156, v105, s42, v176
	v_mad_u32_u24 v157, v105, s42, v176
	v_mad_u32_u24 v188, v107, s42, v98
	v_mad_u32_u24 v189, v108, s42, v98
	v_lshrrev_b32_e32 v111, 1, v98
	v_and_b32_e32 v111, 8, v111
	v_sub_u32_e32 v111, v98, v111
	v_mad_u32_u24 v181, v107, s42, v111
	v_mad_u32_u24 v183, v108, s42, v111
	v_add_u32_e32 v157, 0x9000, v157
	v_add_u32_e32 v181, 0x9000, v181
	v_add_u32_e32 v183, 0x9000, v183
	v_mad_u32_u24 v250, v107, s34, v98
	v_mad_u32_u24 v251, v108, s34, v98
	v_add_u32_e32 v250, 0x4800, v250
	v_add_u32_e32 v251, 0x4800, v251
	ds_read2_b64 v[84:87], v250 offset1:1
	ds_read2_b64 v[80:83], v251 offset1:1
	s_waitcnt lgkmcnt(1)
	ds_write2_b64 v181, v[84:85], v[86:87] offset1:2
	s_waitcnt lgkmcnt(1)
	ds_write2_b64 v183, v[80:81], v[82:83] offset1:2
	s_waitcnt lgkmcnt(0)
	s_barrier
	v_mov_b32_e32 v144, 0
	v_mov_b32_e32 v145, 0
	v_mov_b32_e32 v146, 0
	v_mov_b32_e32 v147, 0
	v_mov_b32_e32 v148, 0
	v_mov_b32_e32 v149, 0
	v_mov_b32_e32 v150, 0
	v_mov_b32_e32 v151, 0
	v_mov_b32_e32 v152, 0
	v_mov_b32_e32 v153, 0
	v_mov_b32_e32 v154, 0
	v_mov_b32_e32 v155, 0
	v_mov_b32_e32 v160, 0
	v_mov_b32_e32 v161, 0
	v_mov_b32_e32 v162, 0
	v_mov_b32_e32 v163, 0
	v_mov_b32_e32 v164, 0
	v_mov_b32_e32 v165, 0
	v_mov_b32_e32 v166, 0
	v_mov_b32_e32 v167, 0
	v_mov_b32_e32 v168, 0
	v_mov_b32_e32 v169, 0
	v_mov_b32_e32 v170, 0
	v_mov_b32_e32 v171, 0
	v_mov_b32_e32 v184, 0
	v_mov_b32_e32 v185, 0
	v_mov_b32_e32 v186, 0
	v_mov_b32_e32 v187, 0
	v_mov_b32_e32 v196, 0
	v_mov_b32_e32 v197, 0
	v_mov_b32_e32 v198, 0
	v_mov_b32_e32 v199, 0
	v_mov_b32_e32 v200, 0
	v_mov_b32_e32 v201, 0
	v_mov_b32_e32 v202, 0
	v_mov_b32_e32 v203, 0
	v_mov_b32_e32 v204, 0
	v_mov_b32_e32 v205, 0
	v_mov_b32_e32 v206, 0
	v_mov_b32_e32 v207, 0
	v_mov_b32_e32 v246, 0
	v_mov_b32_e32 v247, 0
	v_mov_b32_e32 v248, 0
	v_mov_b32_e32 v249, 0
	v_mov_b32_e32 v32, 0xc47a0000
	v_mov_b32_e32 v33, 0xc47a0000
	v_mov_b32_e32 v34, 0xc47a0000
	v_mov_b32_e32 v35, 0xc47a0000
	v_mov_b32_e32 v36, 0xc47a0000
	v_mov_b32_e32 v37, 0xc47a0000
	v_mov_b32_e32 v38, 0xc47a0000
	v_mov_b32_e32 v39, 0xc47a0000
	v_mov_b32_e32 v40, 0xc47a0000
	v_mov_b32_e32 v41, 0xc47a0000
	v_mov_b32_e32 v42, 0xc47a0000
	v_mov_b32_e32 v43, 0xc47a0000
	v_mov_b32_e32 v44, 0xc47a0000
	v_mov_b32_e32 v45, 0xc47a0000
	v_mov_b32_e32 v46, 0xc47a0000
	v_mov_b32_e32 v47, 0xc47a0000
	v_mad_i64_i32 v[104:105], s[6:7], v110, s43, v[96:97]
	v_mad_i64_i32 v[106:107], s[6:7], v109, s43, v[96:97]
.Lgq_top:
	s_and_b32 s1, s0, 64
	s_mul_i32 s6, s1, 0x90
	v_add_u32_e32 v159, s6, v156
	v_add_u32_e32 v172, s6, v157
	ds_read_b128 v[112:115], v159
	ds_read_b128 v[116:119], v159 offset:32
	ds_read_b128 v[120:123], v159 offset:64
	ds_read_b128 v[124:127], v159 offset:96
	ds_read_b128 v[128:131], v159 offset:4608
	ds_read_b128 v[132:135], v159 offset:4640
	ds_read_b128 v[136:139], v159 offset:4672
	ds_read_b128 v[140:143], v159 offset:4704
	s_cmpk_eq_i32 s0, 0x10c0
	s_cbranch_scc1 .Lgq_noload
	s_cmp_lt_u32 s5, 3
	s_cselect_b32 s1, 8, 12
	s_cselect_b32 s6, 0x8000, s8
	s_lshl_b32 s1, s12, s1
	s_add_i32 s1, s6, s1
	s_add_i32 s1, s1, s0
	s_mul_hi_i32 s7, s1, s43
	s_mul_i32 s6, s1, s43
	v_lshl_add_u64 v[250:251], v[104:105], 0, s[6:7]
	global_load_dwordx4 v[92:95], v[250:251], off
	global_load_dwordx4 v[84:87], v[100:101], off
	v_lshl_add_u64 v[250:251], v[106:107], 0, s[6:7]
	global_load_dwordx4 v[88:91], v[250:251], off
	global_load_dwordx4 v[80:83], v[102:103], off
	v_lshl_add_u64 v[100:101], v[100:101], 0, s[10:11]
	v_lshl_add_u64 v[102:103], v[102:103], 0, s[10:11]
